# GEMM loops: all 8 DMA pieces issued right after the barrier (early), with rot8 + out-proj epilogue preloads
# baseline (speedup 1.0000x reference)
.LBB0_263:
	s_and_b32 s15, s14, 0x8000
	s_add_i32 s14, s14, 0x8000
	v_add3_u32 v142, v137, v138, s15
	v_add3_u32 v143, v136, v141, s15
	v_add3_u32 v144, v136, v138, s15
	s_waitcnt lgkmcnt(3)
	v_mfma_f32_16x16x32_bf16 v[124:127], v[174:177], v[158:161], v[124:127]
	v_mfma_f32_16x16x32_bf16 v[92:95], v[178:181], v[158:161], v[92:95]
	v_mfma_f32_16x16x32_bf16 v[60:63], v[182:185], v[158:161], v[60:63]
	v_mfma_f32_16x16x32_bf16 v[28:31], v[186:189], v[158:161], v[28:31]
	ds_read_b128 v[158:161], v143 offset:16384
	ds_read_b128 v[190:193], v142
	s_waitcnt lgkmcnt(4)
	v_mfma_f32_16x16x32_bf16 v[120:123], v[174:177], v[162:165], v[120:123]
	v_mfma_f32_16x16x32_bf16 v[88:91], v[178:181], v[162:165], v[88:91]
	v_mfma_f32_16x16x32_bf16 v[56:59], v[182:185], v[162:165], v[56:59]
	v_mfma_f32_16x16x32_bf16 v[24:27], v[186:189], v[162:165], v[24:27]
	ds_read_b128 v[162:165], v143 offset:18432
	ds_read_b128 v[194:197], v142 offset:2048
	s_waitcnt lgkmcnt(5)
	v_mfma_f32_16x16x32_bf16 v[116:119], v[174:177], v[166:169], v[116:119]
	v_mfma_f32_16x16x32_bf16 v[84:87], v[178:181], v[166:169], v[84:87]
	v_mfma_f32_16x16x32_bf16 v[52:55], v[182:185], v[166:169], v[52:55]
	v_mfma_f32_16x16x32_bf16 v[20:23], v[186:189], v[166:169], v[20:23]
	ds_read_b128 v[166:169], v143 offset:20480
	ds_read_b128 v[198:201], v142 offset:4096
	s_waitcnt lgkmcnt(6)
	v_mfma_f32_16x16x32_bf16 v[112:115], v[174:177], v[170:173], v[112:115]
	v_mfma_f32_16x16x32_bf16 v[80:83], v[178:181], v[170:173], v[80:83]
	v_mfma_f32_16x16x32_bf16 v[48:51], v[182:185], v[170:173], v[48:51]
	v_mfma_f32_16x16x32_bf16 v[16:19], v[186:189], v[170:173], v[16:19]
	ds_read_b128 v[170:173], v143 offset:22528
	ds_read_b128 v[150:153], v142 offset:6144
	s_waitcnt lgkmcnt(7)
	v_mfma_f32_16x16x32_bf16 v[108:111], v[174:177], v[158:161], v[108:111]
	v_mfma_f32_16x16x32_bf16 v[76:79], v[178:181], v[158:161], v[76:79]
	v_mfma_f32_16x16x32_bf16 v[44:47], v[182:185], v[158:161], v[44:47]
	v_mfma_f32_16x16x32_bf16 v[12:15], v[186:189], v[158:161], v[12:15]
	ds_read_b128 v[158:161], v144
	s_waitcnt lgkmcnt(6)
	v_mfma_f32_16x16x32_bf16 v[104:107], v[174:177], v[162:165], v[104:107]
	v_mfma_f32_16x16x32_bf16 v[72:75], v[178:181], v[162:165], v[72:75]
	v_mfma_f32_16x16x32_bf16 v[40:43], v[182:185], v[162:165], v[40:43]
	v_mfma_f32_16x16x32_bf16 v[8:11], v[186:189], v[162:165], v[8:11]
	ds_read_b128 v[162:165], v144 offset:2048
	s_waitcnt lgkmcnt(5)
	v_mfma_f32_16x16x32_bf16 v[100:103], v[174:177], v[166:169], v[100:103]
	v_mfma_f32_16x16x32_bf16 v[68:71], v[178:181], v[166:169], v[68:71]
	v_mfma_f32_16x16x32_bf16 v[36:39], v[182:185], v[166:169], v[36:39]
	v_mfma_f32_16x16x32_bf16 v[4:7], v[186:189], v[166:169], v[4:7]
	ds_read_b128 v[166:169], v144 offset:4096
	s_waitcnt lgkmcnt(4)
	v_mfma_f32_16x16x32_bf16 v[96:99], v[174:177], v[170:173], v[96:99]
	v_mfma_f32_16x16x32_bf16 v[64:67], v[178:181], v[170:173], v[64:67]
	v_mfma_f32_16x16x32_bf16 v[32:35], v[182:185], v[170:173], v[32:35]
	v_mfma_f32_16x16x32_bf16 v[0:3], v[186:189], v[170:173], v[0:3]
	ds_read_b128 v[170:173], v144 offset:6144
	s_waitcnt lgkmcnt(3)
	v_mfma_f32_16x16x32_bf16 v[124:127], v[190:193], v[158:161], v[124:127]
	v_mfma_f32_16x16x32_bf16 v[92:95], v[194:197], v[158:161], v[92:95]
	v_mfma_f32_16x16x32_bf16 v[60:63], v[198:201], v[158:161], v[60:63]
	v_mfma_f32_16x16x32_bf16 v[28:31], v[150:153], v[158:161], v[28:31]
	ds_read_b128 v[158:161], v144 offset:16384
	s_waitcnt lgkmcnt(3)
	v_mfma_f32_16x16x32_bf16 v[120:123], v[190:193], v[162:165], v[120:123]
	v_mfma_f32_16x16x32_bf16 v[88:91], v[194:197], v[162:165], v[88:91]
	v_mfma_f32_16x16x32_bf16 v[56:59], v[198:201], v[162:165], v[56:59]
	v_mfma_f32_16x16x32_bf16 v[24:27], v[150:153], v[162:165], v[24:27]
	ds_read_b128 v[162:165], v144 offset:18432
	s_waitcnt lgkmcnt(3)
	v_mfma_f32_16x16x32_bf16 v[116:119], v[190:193], v[166:169], v[116:119]
	v_mfma_f32_16x16x32_bf16 v[84:87], v[194:197], v[166:169], v[84:87]
	v_mfma_f32_16x16x32_bf16 v[52:55], v[198:201], v[166:169], v[52:55]
	v_mfma_f32_16x16x32_bf16 v[20:23], v[150:153], v[166:169], v[20:23]
	ds_read_b128 v[166:169], v144 offset:20480
	s_waitcnt lgkmcnt(3)
	v_mfma_f32_16x16x32_bf16 v[112:115], v[190:193], v[170:173], v[112:115]
	v_mfma_f32_16x16x32_bf16 v[80:83], v[194:197], v[170:173], v[80:83]
	v_mfma_f32_16x16x32_bf16 v[48:51], v[198:201], v[170:173], v[48:51]
	v_mfma_f32_16x16x32_bf16 v[16:19], v[150:153], v[170:173], v[16:19]
	ds_read_b128 v[170:173], v144 offset:22528
	s_waitcnt lgkmcnt(3)
	v_mfma_f32_16x16x32_bf16 v[108:111], v[190:193], v[158:161], v[108:111]
	v_mfma_f32_16x16x32_bf16 v[76:79], v[194:197], v[158:161], v[76:79]
	v_mfma_f32_16x16x32_bf16 v[44:47], v[198:201], v[158:161], v[44:47]
	v_mfma_f32_16x16x32_bf16 v[12:15], v[150:153], v[158:161], v[12:15]
	s_add_u32 s80, s80, 0x80
	s_addc_u32 s81, s81, 0
	s_cmpk_eq_i32 s80, 0xf80
	s_waitcnt vmcnt(0) lgkmcnt(0)
	s_barrier
	s_cbranch_scc1 .Lgemm_263_exit
	s_xor_b32 s22, s15, 0x8000
	v_add3_u32 v142, v137, v141, s22
	v_add3_u32 v143, v136, v141, s22
	ds_read_b128 v[174:177], v142
	ds_read_b128 v[178:181], v142 offset:2048
	ds_read_b128 v[182:185], v142 offset:4096
	ds_read_b128 v[186:189], v142 offset:6144
	ds_read_b128 v[158:161], v143
	s_add_i32 s100, s98, s15
	s_add_i32 s101, s99, s15
	s_lshr_b32 s22, s23, 3
	s_and_b32 s22, s22, 7
	s_lshl_b32 s22, s22, 9
	s_add_i32 vcc_lo, s80, s22
	s_cmp_ge_u32 vcc_lo, 0xf80
	s_cselect_b32 vcc_hi, 0xf80, 0
	s_sub_i32 vcc_lo, vcc_lo, vcc_hi
	s_add_u32 s82, vcc_lo, 0x7870080
	s_addc_u32 s83, 0, 0
	s_add_i32 m0, s100, 0x0
	v_lshl_add_u64 v[146:147], v[128:129], 0, s[82:83]
	global_load_lds_dwordx4 v[146:147], off
	s_add_u32 s82, vcc_lo, s58
	s_addc_u32 s83, 0, s59
	s_add_i32 m0, s101, 0x0
	v_lshl_add_u64 v[146:147], v[130:131], 0, s[82:83]
	global_load_lds_dwordx4 v[146:147], off
	s_add_u32 s82, vcc_lo, 0x78b0080
	s_addc_u32 s83, 0, 0
	s_add_i32 m0, s100, 0x2000
	v_lshl_add_u64 v[146:147], v[128:129], 0, s[82:83]
	global_load_lds_dwordx4 v[146:147], off
	s_add_u32 s82, vcc_lo, s60
	s_addc_u32 s83, 0, s61
	s_add_i32 m0, s101, 0x2000
	v_lshl_add_u64 v[146:147], v[130:131], 0, s[82:83]
	global_load_lds_dwordx4 v[146:147], off
	s_add_u32 s82, vcc_lo, 0x78f0080
	s_addc_u32 s83, 0, 0
	s_add_i32 m0, s100, 0x4000
	v_lshl_add_u64 v[146:147], v[128:129], 0, s[82:83]
	global_load_lds_dwordx4 v[146:147], off
	s_add_u32 s82, vcc_lo, s62
	s_addc_u32 s83, 0, s63
	s_add_i32 m0, s101, 0x4000
	v_lshl_add_u64 v[146:147], v[130:131], 0, s[82:83]
	global_load_lds_dwordx4 v[146:147], off
	s_add_u32 s82, vcc_lo, 0x7930080
	s_addc_u32 s83, 0, 0
	s_add_i32 m0, s100, 0x6000
	v_lshl_add_u64 v[146:147], v[128:129], 0, s[82:83]
	global_load_lds_dwordx4 v[146:147], off
	s_add_u32 s82, vcc_lo, s64
	s_addc_u32 s83, 0, s65
	s_add_i32 m0, s101, 0x6000
	v_lshl_add_u64 v[146:147], v[130:131], 0, s[82:83]
	global_load_lds_dwordx4 v[146:147], off
	v_mfma_f32_16x16x32_bf16 v[104:107], v[190:193], v[162:165], v[104:107]
	v_mfma_f32_16x16x32_bf16 v[72:75], v[194:197], v[162:165], v[72:75]
	v_mfma_f32_16x16x32_bf16 v[40:43], v[198:201], v[162:165], v[40:43]
	v_mfma_f32_16x16x32_bf16 v[8:11], v[150:153], v[162:165], v[8:11]
	ds_read_b128 v[162:165], v143 offset:2048
	v_mfma_f32_16x16x32_bf16 v[100:103], v[190:193], v[166:169], v[100:103]
	v_mfma_f32_16x16x32_bf16 v[68:71], v[194:197], v[166:169], v[68:71]
	v_mfma_f32_16x16x32_bf16 v[36:39], v[198:201], v[166:169], v[36:39]
	v_mfma_f32_16x16x32_bf16 v[4:7], v[150:153], v[166:169], v[4:7]
	ds_read_b128 v[166:169], v143 offset:4096
	v_mfma_f32_16x16x32_bf16 v[96:99], v[190:193], v[170:173], v[96:99]
	v_mfma_f32_16x16x32_bf16 v[64:67], v[194:197], v[170:173], v[64:67]
	v_mfma_f32_16x16x32_bf16 v[32:35], v[198:201], v[170:173], v[32:35]
	v_mfma_f32_16x16x32_bf16 v[0:3], v[150:153], v[170:173], v[0:3]
	ds_read_b128 v[170:173], v143 offset:6144
	s_branch .LBB0_263

.LBB0_496:
	s_and_b32 s70, s4, 0x8000
	s_add_i32 s4, s4, 0x8000
	v_add3_u32 v143, v137, v138, s70
	v_add3_u32 v157, v139, v142, s70
	v_add3_u32 v186, v139, v138, s70
	s_waitcnt lgkmcnt(3)
	v_mfma_f32_16x16x32_bf16 v[124:127], v[174:177], v[158:161], v[124:127]
	v_mfma_f32_16x16x32_bf16 v[96:99], v[178:181], v[158:161], v[96:99]
	v_mfma_f32_16x16x32_bf16 v[72:75], v[182:185], v[158:161], v[72:75]
	v_mfma_f32_16x16x32_bf16 v[48:51], v[144:147], v[158:161], v[48:51]
	ds_read_b128 v[158:161], v157 offset:16384
	ds_read_b128 v[148:151], v143
	s_waitcnt lgkmcnt(4)
	v_mfma_f32_16x16x32_bf16 v[120:123], v[174:177], v[162:165], v[120:123]
	v_mfma_f32_16x16x32_bf16 v[92:95], v[178:181], v[162:165], v[92:95]
	v_mfma_f32_16x16x32_bf16 v[68:71], v[182:185], v[162:165], v[68:71]
	v_mfma_f32_16x16x32_bf16 v[44:47], v[144:147], v[162:165], v[44:47]
	ds_read_b128 v[162:165], v157 offset:18432
	ds_read_b128 v[152:155], v143 offset:2048
	s_waitcnt lgkmcnt(5)
	v_mfma_f32_16x16x32_bf16 v[116:119], v[174:177], v[166:169], v[116:119]
	v_mfma_f32_16x16x32_bf16 v[88:91], v[178:181], v[166:169], v[88:91]
	v_mfma_f32_16x16x32_bf16 v[64:67], v[182:185], v[166:169], v[64:67]
	v_mfma_f32_16x16x32_bf16 v[40:43], v[144:147], v[166:169], v[40:43]
	ds_read_b128 v[166:169], v157 offset:20480
	ds_read_b128 v[244:247], v143 offset:4096
	s_waitcnt lgkmcnt(6)
	v_mfma_f32_16x16x32_bf16 v[112:115], v[174:177], v[170:173], v[112:115]
	v_mfma_f32_16x16x32_bf16 v[84:87], v[178:181], v[170:173], v[84:87]
	v_mfma_f32_16x16x32_bf16 v[60:63], v[182:185], v[170:173], v[60:63]
	v_mfma_f32_16x16x32_bf16 v[36:39], v[144:147], v[170:173], v[36:39]
	ds_read_b128 v[170:173], v157 offset:22528
	ds_read_b128 v[248:251], v143 offset:6144
	s_waitcnt lgkmcnt(7)
	v_mfma_f32_16x16x32_bf16 v[108:111], v[174:177], v[158:161], v[108:111]
	v_mfma_f32_16x16x32_bf16 v[80:83], v[178:181], v[158:161], v[80:83]
	v_mfma_f32_16x16x32_bf16 v[56:59], v[182:185], v[158:161], v[56:59]
	v_mfma_f32_16x16x32_bf16 v[32:35], v[144:147], v[158:161], v[32:35]
	ds_read_b128 v[158:161], v186
	s_waitcnt lgkmcnt(6)
	v_mfma_f32_16x16x32_bf16 v[28:31], v[174:177], v[162:165], v[28:31]
	v_mfma_f32_16x16x32_bf16 v[16:19], v[178:181], v[162:165], v[16:19]
	v_mfma_f32_16x16x32_bf16 v[8:11], v[182:185], v[162:165], v[8:11]
	v_mfma_f32_16x16x32_bf16 v[0:3], v[144:147], v[162:165], v[0:3]
	ds_read_b128 v[162:165], v186 offset:2048
	s_waitcnt lgkmcnt(5)
	v_mfma_f32_16x16x32_bf16 v[104:107], v[174:177], v[166:169], v[104:107]
	v_mfma_f32_16x16x32_bf16 v[76:79], v[178:181], v[166:169], v[76:79]
	v_mfma_f32_16x16x32_bf16 v[52:55], v[182:185], v[166:169], v[52:55]
	v_mfma_f32_16x16x32_bf16 v[100:103], v[144:147], v[166:169], v[100:103]
	ds_read_b128 v[166:169], v186 offset:4096
	s_waitcnt lgkmcnt(4)
	v_mfma_f32_16x16x32_bf16 v[24:27], v[174:177], v[170:173], v[24:27]
	v_mfma_f32_16x16x32_bf16 v[12:15], v[178:181], v[170:173], v[12:15]
	v_mfma_f32_16x16x32_bf16 v[4:7], v[182:185], v[170:173], v[4:7]
	v_mfma_f32_16x16x32_bf16 v[20:23], v[144:147], v[170:173], v[20:23]
	ds_read_b128 v[170:173], v186 offset:6144
	s_waitcnt lgkmcnt(3)
	v_mfma_f32_16x16x32_bf16 v[124:127], v[148:151], v[158:161], v[124:127]
	v_mfma_f32_16x16x32_bf16 v[96:99], v[152:155], v[158:161], v[96:99]
	v_mfma_f32_16x16x32_bf16 v[72:75], v[244:247], v[158:161], v[72:75]
	v_mfma_f32_16x16x32_bf16 v[48:51], v[248:251], v[158:161], v[48:51]
	ds_read_b128 v[158:161], v186 offset:16384
	s_waitcnt lgkmcnt(3)
	v_mfma_f32_16x16x32_bf16 v[120:123], v[148:151], v[162:165], v[120:123]
	v_mfma_f32_16x16x32_bf16 v[92:95], v[152:155], v[162:165], v[92:95]
	v_mfma_f32_16x16x32_bf16 v[68:71], v[244:247], v[162:165], v[68:71]
	v_mfma_f32_16x16x32_bf16 v[44:47], v[248:251], v[162:165], v[44:47]
	ds_read_b128 v[162:165], v186 offset:18432
	s_waitcnt lgkmcnt(3)
	v_mfma_f32_16x16x32_bf16 v[116:119], v[148:151], v[166:169], v[116:119]
	v_mfma_f32_16x16x32_bf16 v[88:91], v[152:155], v[166:169], v[88:91]
	v_mfma_f32_16x16x32_bf16 v[64:67], v[244:247], v[166:169], v[64:67]
	v_mfma_f32_16x16x32_bf16 v[40:43], v[248:251], v[166:169], v[40:43]
	ds_read_b128 v[166:169], v186 offset:20480
	s_waitcnt lgkmcnt(3)
	v_mfma_f32_16x16x32_bf16 v[112:115], v[148:151], v[170:173], v[112:115]
	v_mfma_f32_16x16x32_bf16 v[84:87], v[152:155], v[170:173], v[84:87]
	v_mfma_f32_16x16x32_bf16 v[60:63], v[244:247], v[170:173], v[60:63]
	v_mfma_f32_16x16x32_bf16 v[36:39], v[248:251], v[170:173], v[36:39]
	ds_read_b128 v[170:173], v186 offset:22528
	s_waitcnt lgkmcnt(3)
	v_mfma_f32_16x16x32_bf16 v[108:111], v[148:151], v[158:161], v[108:111]
	v_mfma_f32_16x16x32_bf16 v[80:83], v[152:155], v[158:161], v[80:83]
	v_mfma_f32_16x16x32_bf16 v[56:59], v[244:247], v[158:161], v[56:59]
	v_mfma_f32_16x16x32_bf16 v[32:35], v[248:251], v[158:161], v[32:35]
	s_add_u32 s62, s62, 0x80
	s_addc_u32 s63, s63, 0
	s_cmpk_eq_i32 s62, 0xf80
	s_waitcnt vmcnt(0) lgkmcnt(0)
	s_barrier
	s_cbranch_scc1 .Lgemm_496_exit
	s_xor_b32 s71, s70, 0x8000
	v_add3_u32 v143, v137, v142, s71
	v_add3_u32 v157, v139, v142, s71
	ds_read_b128 v[174:177], v143
	ds_read_b128 v[178:181], v143 offset:2048
	ds_read_b128 v[182:185], v143 offset:4096
	ds_read_b128 v[144:147], v143 offset:6144
	ds_read_b128 v[158:161], v157
	s_add_i32 s76, s66, s70
	s_add_i32 s77, s67, s70
	s_lshr_b32 s71, s23, 3
	s_and_b32 s71, s71, 31
	s_cmp_eq_u32 s71, 31
	s_cselect_b32 s71, 0, s71
	s_lshl_b32 s71, s71, 7
	s_add_i32 vcc_lo, s62, s71
	s_cmp_ge_u32 vcc_lo, 0xf80
	s_cselect_b32 vcc_hi, 0xf80, 0
	s_sub_i32 vcc_lo, vcc_lo, vcc_hi
	s_add_u32 s68, vcc_lo, s38
	s_addc_u32 s69, 0, s39
	s_add_i32 m0, s76, 0x0
	v_lshl_add_u64 v[242:243], v[128:129], 0, s[68:69]
	global_load_lds_dwordx4 v[242:243], off
	s_add_u32 s68, vcc_lo, s40
	s_addc_u32 s69, 0, s41
	s_add_i32 m0, s77, 0x0
	v_lshl_add_u64 v[242:243], v[130:131], 0, s[68:69]
	global_load_lds_dwordx4 v[242:243], off
	s_add_u32 s68, vcc_lo, s44
	s_addc_u32 s69, 0, s45
	s_add_i32 m0, s76, 0x2000
	v_lshl_add_u64 v[242:243], v[128:129], 0, s[68:69]
	global_load_lds_dwordx4 v[242:243], off
	s_add_u32 s68, vcc_lo, s48
	s_addc_u32 s69, 0, s49
	s_add_i32 m0, s77, 0x2000
	v_lshl_add_u64 v[242:243], v[130:131], 0, s[68:69]
	global_load_lds_dwordx4 v[242:243], off
	s_add_u32 s68, vcc_lo, s50
	s_addc_u32 s69, 0, s51
	s_add_i32 m0, s76, 0x4000
	v_lshl_add_u64 v[242:243], v[128:129], 0, s[68:69]
	global_load_lds_dwordx4 v[242:243], off
	s_add_u32 s68, vcc_lo, s54
	s_addc_u32 s69, 0, s55
	s_add_i32 m0, s77, 0x4000
	v_lshl_add_u64 v[242:243], v[130:131], 0, s[68:69]
	global_load_lds_dwordx4 v[242:243], off
	s_add_u32 s68, vcc_lo, s56
	s_addc_u32 s69, 0, s57
	s_add_i32 m0, s76, 0x6000
	v_lshl_add_u64 v[242:243], v[128:129], 0, s[68:69]
	global_load_lds_dwordx4 v[242:243], off
	s_add_u32 s68, vcc_lo, s58
	s_addc_u32 s69, 0, s59
	s_add_i32 m0, s77, 0x6000
	v_lshl_add_u64 v[242:243], v[130:131], 0, s[68:69]
	global_load_lds_dwordx4 v[242:243], off
	v_mfma_f32_16x16x32_bf16 v[28:31], v[148:151], v[162:165], v[28:31]
	v_mfma_f32_16x16x32_bf16 v[16:19], v[152:155], v[162:165], v[16:19]
	v_mfma_f32_16x16x32_bf16 v[8:11], v[244:247], v[162:165], v[8:11]
	v_mfma_f32_16x16x32_bf16 v[0:3], v[248:251], v[162:165], v[0:3]
	ds_read_b128 v[162:165], v157 offset:2048
	v_mfma_f32_16x16x32_bf16 v[104:107], v[148:151], v[166:169], v[104:107]
	v_mfma_f32_16x16x32_bf16 v[76:79], v[152:155], v[166:169], v[76:79]
	v_mfma_f32_16x16x32_bf16 v[52:55], v[244:247], v[166:169], v[52:55]
	v_mfma_f32_16x16x32_bf16 v[100:103], v[248:251], v[166:169], v[100:103]
	ds_read_b128 v[166:169], v157 offset:4096
	v_mfma_f32_16x16x32_bf16 v[24:27], v[148:151], v[170:173], v[24:27]
	v_mfma_f32_16x16x32_bf16 v[12:15], v[152:155], v[170:173], v[12:15]
	v_mfma_f32_16x16x32_bf16 v[4:7], v[244:247], v[170:173], v[4:7]
	v_mfma_f32_16x16x32_bf16 v[20:23], v[248:251], v[170:173], v[20:23]
	ds_read_b128 v[170:173], v157 offset:6144
	s_branch .LBB0_496

.LBB0_621:
	s_and_b32 s68, s60, 0x8000
	s_add_i32 s60, s60, 0x8000
	v_add3_u32 v143, v137, v138, s68
	v_add3_u32 v157, v139, v140, s68
	v_add3_u32 v186, v139, v138, s68
	s_waitcnt lgkmcnt(3)
	v_mfma_f32_16x16x32_bf16 v[124:127], v[174:177], v[158:161], v[124:127]
	v_mfma_f32_16x16x32_bf16 v[108:111], v[178:181], v[158:161], v[108:111]
	v_mfma_f32_16x16x32_bf16 v[92:95], v[182:185], v[158:161], v[92:95]
	v_mfma_f32_16x16x32_bf16 v[76:79], v[144:147], v[158:161], v[76:79]
	ds_read_b128 v[158:161], v157 offset:16384
	ds_read_b128 v[148:151], v143
	s_waitcnt lgkmcnt(4)
	v_mfma_f32_16x16x32_bf16 v[120:123], v[174:177], v[162:165], v[120:123]
	v_mfma_f32_16x16x32_bf16 v[104:107], v[178:181], v[162:165], v[104:107]
	v_mfma_f32_16x16x32_bf16 v[88:91], v[182:185], v[162:165], v[88:91]
	v_mfma_f32_16x16x32_bf16 v[72:75], v[144:147], v[162:165], v[72:75]
	ds_read_b128 v[162:165], v157 offset:18432
	ds_read_b128 v[152:155], v143 offset:2048
	s_waitcnt lgkmcnt(5)
	v_mfma_f32_16x16x32_bf16 v[116:119], v[174:177], v[166:169], v[116:119]
	v_mfma_f32_16x16x32_bf16 v[100:103], v[178:181], v[166:169], v[100:103]
	v_mfma_f32_16x16x32_bf16 v[84:87], v[182:185], v[166:169], v[84:87]
	v_mfma_f32_16x16x32_bf16 v[68:71], v[144:147], v[166:169], v[68:71]
	ds_read_b128 v[166:169], v157 offset:20480
	ds_read_b128 v[244:247], v143 offset:4096
	s_waitcnt lgkmcnt(6)
	v_mfma_f32_16x16x32_bf16 v[112:115], v[174:177], v[170:173], v[112:115]
	v_mfma_f32_16x16x32_bf16 v[96:99], v[178:181], v[170:173], v[96:99]
	v_mfma_f32_16x16x32_bf16 v[80:83], v[182:185], v[170:173], v[80:83]
	v_mfma_f32_16x16x32_bf16 v[64:67], v[144:147], v[170:173], v[64:67]
	ds_read_b128 v[170:173], v157 offset:22528
	ds_read_b128 v[248:251], v143 offset:6144
	s_waitcnt lgkmcnt(7)
	v_mfma_f32_16x16x32_bf16 v[60:63], v[174:177], v[158:161], v[60:63]
	v_mfma_f32_16x16x32_bf16 v[48:51], v[178:181], v[158:161], v[48:51]
	v_mfma_f32_16x16x32_bf16 v[40:43], v[182:185], v[158:161], v[40:43]
	v_mfma_f32_16x16x32_bf16 v[32:35], v[144:147], v[158:161], v[32:35]
	ds_read_b128 v[158:161], v186
	s_waitcnt lgkmcnt(6)
	v_mfma_f32_16x16x32_bf16 v[28:31], v[174:177], v[162:165], v[28:31]
	v_mfma_f32_16x16x32_bf16 v[16:19], v[178:181], v[162:165], v[16:19]
	v_mfma_f32_16x16x32_bf16 v[8:11], v[182:185], v[162:165], v[8:11]
	v_mfma_f32_16x16x32_bf16 v[0:3], v[144:147], v[162:165], v[0:3]
	ds_read_b128 v[162:165], v186 offset:2048
	s_waitcnt lgkmcnt(5)
	v_mfma_f32_16x16x32_bf16 v[52:55], v[174:177], v[166:169], v[52:55]
	v_mfma_f32_16x16x32_bf16 v[44:47], v[178:181], v[166:169], v[44:47]
	v_mfma_f32_16x16x32_bf16 v[36:39], v[182:185], v[166:169], v[36:39]
	v_mfma_f32_16x16x32_bf16 v[56:59], v[144:147], v[166:169], v[56:59]
	ds_read_b128 v[166:169], v186 offset:4096
	s_waitcnt lgkmcnt(4)
	v_mfma_f32_16x16x32_bf16 v[24:27], v[174:177], v[170:173], v[24:27]
	v_mfma_f32_16x16x32_bf16 v[12:15], v[178:181], v[170:173], v[12:15]
	v_mfma_f32_16x16x32_bf16 v[4:7], v[182:185], v[170:173], v[4:7]
	v_mfma_f32_16x16x32_bf16 v[20:23], v[144:147], v[170:173], v[20:23]
	ds_read_b128 v[170:173], v186 offset:6144
	s_waitcnt lgkmcnt(3)
	v_mfma_f32_16x16x32_bf16 v[124:127], v[148:151], v[158:161], v[124:127]
	v_mfma_f32_16x16x32_bf16 v[108:111], v[152:155], v[158:161], v[108:111]
	v_mfma_f32_16x16x32_bf16 v[92:95], v[244:247], v[158:161], v[92:95]
	v_mfma_f32_16x16x32_bf16 v[76:79], v[248:251], v[158:161], v[76:79]
	ds_read_b128 v[158:161], v186 offset:16384
	s_waitcnt lgkmcnt(3)
	v_mfma_f32_16x16x32_bf16 v[120:123], v[148:151], v[162:165], v[120:123]
	v_mfma_f32_16x16x32_bf16 v[104:107], v[152:155], v[162:165], v[104:107]
	v_mfma_f32_16x16x32_bf16 v[88:91], v[244:247], v[162:165], v[88:91]
	v_mfma_f32_16x16x32_bf16 v[72:75], v[248:251], v[162:165], v[72:75]
	ds_read_b128 v[162:165], v186 offset:18432
	s_waitcnt lgkmcnt(3)
	v_mfma_f32_16x16x32_bf16 v[116:119], v[148:151], v[166:169], v[116:119]
	v_mfma_f32_16x16x32_bf16 v[100:103], v[152:155], v[166:169], v[100:103]
	v_mfma_f32_16x16x32_bf16 v[84:87], v[244:247], v[166:169], v[84:87]
	v_mfma_f32_16x16x32_bf16 v[68:71], v[248:251], v[166:169], v[68:71]
	ds_read_b128 v[166:169], v186 offset:20480
	s_waitcnt lgkmcnt(3)
	v_mfma_f32_16x16x32_bf16 v[112:115], v[148:151], v[170:173], v[112:115]
	v_mfma_f32_16x16x32_bf16 v[96:99], v[152:155], v[170:173], v[96:99]
	v_mfma_f32_16x16x32_bf16 v[80:83], v[244:247], v[170:173], v[80:83]
	v_mfma_f32_16x16x32_bf16 v[64:67], v[248:251], v[170:173], v[64:67]
	ds_read_b128 v[170:173], v186 offset:22528
	s_waitcnt lgkmcnt(3)
	v_mfma_f32_16x16x32_bf16 v[60:63], v[148:151], v[158:161], v[60:63]
	v_mfma_f32_16x16x32_bf16 v[48:51], v[152:155], v[158:161], v[48:51]
	v_mfma_f32_16x16x32_bf16 v[40:43], v[244:247], v[158:161], v[40:43]
	v_mfma_f32_16x16x32_bf16 v[32:35], v[248:251], v[158:161], v[32:35]
	s_add_u32 s4, s4, 0x80
	s_addc_u32 s5, s5, 0
	s_cmpk_eq_i32 s4, 0xf80
	s_waitcnt vmcnt(0) lgkmcnt(0)
	s_barrier
	s_cbranch_scc1 .Lgemm_621_exit
	s_xor_b32 s69, s68, 0x8000
	v_add3_u32 v143, v137, v140, s69
	v_add3_u32 v157, v139, v140, s69
	ds_read_b128 v[174:177], v143
	ds_read_b128 v[178:181], v143 offset:2048
	ds_read_b128 v[182:185], v143 offset:4096
	ds_read_b128 v[144:147], v143 offset:6144
	ds_read_b128 v[158:161], v157
	s_add_i32 s70, s64, s68
	s_add_i32 s71, s65, s68
	s_lshr_b32 s69, s23, 3
	s_and_b32 s69, s69, 7
	s_lshl_b32 s69, s69, 9
	s_add_i32 vcc_lo, s4, s69
	s_cmp_ge_u32 vcc_lo, 0xf80
	s_cselect_b32 vcc_hi, 0xf80, 0
	s_sub_i32 vcc_lo, vcc_lo, vcc_hi
	s_add_u32 s66, vcc_lo, s36
	s_addc_u32 s67, 0, s37
	s_add_i32 m0, s70, 0x0
	v_lshl_add_u64 v[242:243], v[128:129], 0, s[66:67]
	global_load_lds_dwordx4 v[242:243], off
	s_add_u32 s66, vcc_lo, s38
	s_addc_u32 s67, 0, s39
	s_add_i32 m0, s71, 0x0
	v_lshl_add_u64 v[242:243], v[130:131], 0, s[66:67]
	global_load_lds_dwordx4 v[242:243], off
	s_add_u32 s66, vcc_lo, s40
	s_addc_u32 s67, 0, s41
	s_add_i32 m0, s70, 0x2000
	v_lshl_add_u64 v[242:243], v[128:129], 0, s[66:67]
	global_load_lds_dwordx4 v[242:243], off
	s_add_u32 s66, vcc_lo, s42
	s_addc_u32 s67, 0, s43
	s_add_i32 m0, s71, 0x2000
	v_lshl_add_u64 v[242:243], v[130:131], 0, s[66:67]
	global_load_lds_dwordx4 v[242:243], off
	s_add_u32 s66, vcc_lo, s44
	s_addc_u32 s67, 0, s45
	s_add_i32 m0, s70, 0x4000
	v_lshl_add_u64 v[242:243], v[128:129], 0, s[66:67]
	global_load_lds_dwordx4 v[242:243], off
	s_add_u32 s66, vcc_lo, s48
	s_addc_u32 s67, 0, s49
	s_add_i32 m0, s71, 0x4000
	v_lshl_add_u64 v[242:243], v[130:131], 0, s[66:67]
	global_load_lds_dwordx4 v[242:243], off
	s_add_u32 s66, vcc_lo, s50
	s_addc_u32 s67, 0, s51
	s_add_i32 m0, s70, 0x6000
	v_lshl_add_u64 v[242:243], v[128:129], 0, s[66:67]
	global_load_lds_dwordx4 v[242:243], off
	s_add_u32 s66, vcc_lo, s54
	s_addc_u32 s67, 0, s55
	s_add_i32 m0, s71, 0x6000
	v_lshl_add_u64 v[242:243], v[130:131], 0, s[66:67]
	global_load_lds_dwordx4 v[242:243], off
	v_mfma_f32_16x16x32_bf16 v[28:31], v[148:151], v[162:165], v[28:31]
	v_mfma_f32_16x16x32_bf16 v[16:19], v[152:155], v[162:165], v[16:19]
	v_mfma_f32_16x16x32_bf16 v[8:11], v[244:247], v[162:165], v[8:11]
	v_mfma_f32_16x16x32_bf16 v[0:3], v[248:251], v[162:165], v[0:3]
	ds_read_b128 v[162:165], v157 offset:2048
	v_mfma_f32_16x16x32_bf16 v[52:55], v[148:151], v[166:169], v[52:55]
	v_mfma_f32_16x16x32_bf16 v[44:47], v[152:155], v[166:169], v[44:47]
	v_mfma_f32_16x16x32_bf16 v[36:39], v[244:247], v[166:169], v[36:39]
	v_mfma_f32_16x16x32_bf16 v[56:59], v[248:251], v[166:169], v[56:59]
	ds_read_b128 v[166:169], v157 offset:4096
	v_mfma_f32_16x16x32_bf16 v[24:27], v[148:151], v[170:173], v[24:27]
	v_mfma_f32_16x16x32_bf16 v[12:15], v[152:155], v[170:173], v[12:15]
	v_mfma_f32_16x16x32_bf16 v[4:7], v[244:247], v[170:173], v[4:7]
	v_mfma_f32_16x16x32_bf16 v[20:23], v[248:251], v[170:173], v[20:23]
	ds_read_b128 v[170:173], v157 offset:6144
	s_branch .LBB0_621

.LBB0_698:
	s_and_b32 s59, s2, 0x8000
	s_add_i32 s2, s2, 0x8000
	v_add3_u32 v157, v138, v139, s59
	v_add3_u32 v186, v140, v143, s59
	v_add3_u32 v187, v140, v139, s59
	s_waitcnt lgkmcnt(3)
	v_mfma_f32_16x16x32_bf16 v[124:127], v[174:177], v[158:161], v[124:127]
	v_mfma_f32_16x16x32_bf16 v[108:111], v[178:181], v[158:161], v[108:111]
	v_mfma_f32_16x16x32_bf16 v[92:95], v[182:185], v[158:161], v[92:95]
	v_mfma_f32_16x16x32_bf16 v[76:79], v[144:147], v[158:161], v[76:79]
	ds_read_b128 v[158:161], v186 offset:16384
	ds_read_b128 v[148:151], v157
	s_waitcnt lgkmcnt(4)
	v_mfma_f32_16x16x32_bf16 v[120:123], v[174:177], v[162:165], v[120:123]
	v_mfma_f32_16x16x32_bf16 v[104:107], v[178:181], v[162:165], v[104:107]
	v_mfma_f32_16x16x32_bf16 v[88:91], v[182:185], v[162:165], v[88:91]
	v_mfma_f32_16x16x32_bf16 v[72:75], v[144:147], v[162:165], v[72:75]
	ds_read_b128 v[162:165], v186 offset:18432
	ds_read_b128 v[152:155], v157 offset:2048
	s_waitcnt lgkmcnt(5)
	v_mfma_f32_16x16x32_bf16 v[116:119], v[174:177], v[166:169], v[116:119]
	v_mfma_f32_16x16x32_bf16 v[100:103], v[178:181], v[166:169], v[100:103]
	v_mfma_f32_16x16x32_bf16 v[84:87], v[182:185], v[166:169], v[84:87]
	v_mfma_f32_16x16x32_bf16 v[68:71], v[144:147], v[166:169], v[68:71]
	ds_read_b128 v[166:169], v186 offset:20480
	ds_read_b128 v[244:247], v157 offset:4096
	s_waitcnt lgkmcnt(6)
	v_mfma_f32_16x16x32_bf16 v[112:115], v[174:177], v[170:173], v[112:115]
	v_mfma_f32_16x16x32_bf16 v[96:99], v[178:181], v[170:173], v[96:99]
	v_mfma_f32_16x16x32_bf16 v[80:83], v[182:185], v[170:173], v[80:83]
	v_mfma_f32_16x16x32_bf16 v[64:67], v[144:147], v[170:173], v[64:67]
	ds_read_b128 v[170:173], v186 offset:22528
	ds_read_b128 v[248:251], v157 offset:6144
	s_waitcnt lgkmcnt(7)
	v_mfma_f32_16x16x32_bf16 v[60:63], v[174:177], v[158:161], v[60:63]
	v_mfma_f32_16x16x32_bf16 v[36:39], v[178:181], v[158:161], v[36:39]
	v_mfma_f32_16x16x32_bf16 v[20:23], v[182:185], v[158:161], v[20:23]
	v_mfma_f32_16x16x32_bf16 v[4:7], v[144:147], v[158:161], v[4:7]
	ds_read_b128 v[158:161], v187
	s_waitcnt lgkmcnt(6)
	v_mfma_f32_16x16x32_bf16 v[56:59], v[174:177], v[162:165], v[56:59]
	v_mfma_f32_16x16x32_bf16 v[32:35], v[178:181], v[162:165], v[32:35]
	v_mfma_f32_16x16x32_bf16 v[16:19], v[182:185], v[162:165], v[16:19]
	v_mfma_f32_16x16x32_bf16 v[0:3], v[144:147], v[162:165], v[0:3]
	ds_read_b128 v[162:165], v187 offset:2048
	s_waitcnt lgkmcnt(5)
	v_mfma_f32_16x16x32_bf16 v[52:55], v[174:177], v[166:169], v[52:55]
	v_mfma_f32_16x16x32_bf16 v[28:31], v[178:181], v[166:169], v[28:31]
	v_mfma_f32_16x16x32_bf16 v[12:15], v[182:185], v[166:169], v[12:15]
	v_mfma_f32_16x16x32_bf16 v[44:47], v[144:147], v[166:169], v[44:47]
	ds_read_b128 v[166:169], v187 offset:4096
	s_waitcnt lgkmcnt(4)
	v_mfma_f32_16x16x32_bf16 v[48:51], v[174:177], v[170:173], v[48:51]
	v_mfma_f32_16x16x32_bf16 v[24:27], v[178:181], v[170:173], v[24:27]
	v_mfma_f32_16x16x32_bf16 v[8:11], v[182:185], v[170:173], v[8:11]
	v_mfma_f32_16x16x32_bf16 v[40:43], v[144:147], v[170:173], v[40:43]
	ds_read_b128 v[170:173], v187 offset:6144
	s_waitcnt lgkmcnt(3)
	v_mfma_f32_16x16x32_bf16 v[124:127], v[148:151], v[158:161], v[124:127]
	v_mfma_f32_16x16x32_bf16 v[108:111], v[152:155], v[158:161], v[108:111]
	v_mfma_f32_16x16x32_bf16 v[92:95], v[244:247], v[158:161], v[92:95]
	v_mfma_f32_16x16x32_bf16 v[76:79], v[248:251], v[158:161], v[76:79]
	ds_read_b128 v[158:161], v187 offset:16384
	s_waitcnt lgkmcnt(3)
	v_mfma_f32_16x16x32_bf16 v[120:123], v[148:151], v[162:165], v[120:123]
	v_mfma_f32_16x16x32_bf16 v[104:107], v[152:155], v[162:165], v[104:107]
	v_mfma_f32_16x16x32_bf16 v[88:91], v[244:247], v[162:165], v[88:91]
	v_mfma_f32_16x16x32_bf16 v[72:75], v[248:251], v[162:165], v[72:75]
	ds_read_b128 v[162:165], v187 offset:18432
	s_waitcnt lgkmcnt(3)
	v_mfma_f32_16x16x32_bf16 v[116:119], v[148:151], v[166:169], v[116:119]
	v_mfma_f32_16x16x32_bf16 v[100:103], v[152:155], v[166:169], v[100:103]
	v_mfma_f32_16x16x32_bf16 v[84:87], v[244:247], v[166:169], v[84:87]
	v_mfma_f32_16x16x32_bf16 v[68:71], v[248:251], v[166:169], v[68:71]
	ds_read_b128 v[166:169], v187 offset:20480
	s_waitcnt lgkmcnt(3)
	v_mfma_f32_16x16x32_bf16 v[112:115], v[148:151], v[170:173], v[112:115]
	v_mfma_f32_16x16x32_bf16 v[96:99], v[152:155], v[170:173], v[96:99]
	v_mfma_f32_16x16x32_bf16 v[80:83], v[244:247], v[170:173], v[80:83]
	v_mfma_f32_16x16x32_bf16 v[64:67], v[248:251], v[170:173], v[64:67]
	ds_read_b128 v[170:173], v187 offset:22528
	s_waitcnt lgkmcnt(3)
	v_mfma_f32_16x16x32_bf16 v[60:63], v[148:151], v[158:161], v[60:63]
	v_mfma_f32_16x16x32_bf16 v[36:39], v[152:155], v[158:161], v[36:39]
	v_mfma_f32_16x16x32_bf16 v[20:23], v[244:247], v[158:161], v[20:23]
	v_mfma_f32_16x16x32_bf16 v[4:7], v[248:251], v[158:161], v[4:7]
	s_add_u32 s52, s52, 0x80
	s_addc_u32 s53, s53, 0
	s_cmpk_eq_i32 s52, 0xf80
	s_waitcnt vmcnt(0) lgkmcnt(0)
	s_barrier
	s_cbranch_scc1 .Lgemm_698_exit
	s_xor_b32 s62, s59, 0x8000
	v_add3_u32 v157, v138, v143, s62
	v_add3_u32 v186, v140, v143, s62
	ds_read_b128 v[174:177], v157
	ds_read_b128 v[178:181], v157 offset:2048
	ds_read_b128 v[182:185], v157 offset:4096
	ds_read_b128 v[144:147], v157 offset:6144
	ds_read_b128 v[158:161], v186
	s_add_i32 s63, s57, s59
	s_add_i32 s64, s58, s59
	s_lshr_b32 s62, s23, 3
	s_and_b32 s62, s62, 7
	s_lshl_b32 s62, s62, 9
	s_add_i32 vcc_lo, s52, s62
	s_cmp_ge_u32 vcc_lo, 0xf80
	s_cselect_b32 vcc_hi, 0xf80, 0
	s_sub_i32 vcc_lo, vcc_lo, vcc_hi
	s_add_u32 s60, vcc_lo, s24
	s_addc_u32 s61, 0, s25
	s_add_i32 m0, s63, 0x0
	v_lshl_add_u64 v[242:243], v[130:131], 0, s[60:61]
	global_load_lds_dwordx4 v[242:243], off
	s_add_u32 s60, vcc_lo, s26
	s_addc_u32 s61, 0, s27
	s_add_i32 m0, s64, 0x0
	v_lshl_add_u64 v[242:243], v[132:133], 0, s[60:61]
	global_load_lds_dwordx4 v[242:243], off
	s_add_u32 s60, vcc_lo, s36
	s_addc_u32 s61, 0, s37
	s_add_i32 m0, s63, 0x2000
	v_lshl_add_u64 v[242:243], v[130:131], 0, s[60:61]
	global_load_lds_dwordx4 v[242:243], off
	s_add_u32 s60, vcc_lo, s38
	s_addc_u32 s61, 0, s39
	s_add_i32 m0, s64, 0x2000
	v_lshl_add_u64 v[242:243], v[132:133], 0, s[60:61]
	global_load_lds_dwordx4 v[242:243], off
	s_add_u32 s60, vcc_lo, s40
	s_addc_u32 s61, 0, s41
	s_add_i32 m0, s63, 0x4000
	v_lshl_add_u64 v[242:243], v[130:131], 0, s[60:61]
	global_load_lds_dwordx4 v[242:243], off
	s_add_u32 s60, vcc_lo, s42
	s_addc_u32 s61, 0, s43
	s_add_i32 m0, s64, 0x4000
	v_lshl_add_u64 v[242:243], v[132:133], 0, s[60:61]
	global_load_lds_dwordx4 v[242:243], off
	s_add_u32 s60, vcc_lo, s44
	s_addc_u32 s61, 0, s45
	s_add_i32 m0, s63, 0x6000
	v_lshl_add_u64 v[242:243], v[130:131], 0, s[60:61]
	global_load_lds_dwordx4 v[242:243], off
	s_add_u32 s60, vcc_lo, s48
	s_addc_u32 s61, 0, s49
	s_add_i32 m0, s64, 0x6000
	v_lshl_add_u64 v[242:243], v[132:133], 0, s[60:61]
	global_load_lds_dwordx4 v[242:243], off
	v_mfma_f32_16x16x32_bf16 v[56:59], v[148:151], v[162:165], v[56:59]
	v_mfma_f32_16x16x32_bf16 v[32:35], v[152:155], v[162:165], v[32:35]
	v_mfma_f32_16x16x32_bf16 v[16:19], v[244:247], v[162:165], v[16:19]
	v_mfma_f32_16x16x32_bf16 v[0:3], v[248:251], v[162:165], v[0:3]
	ds_read_b128 v[162:165], v186 offset:2048
	v_mfma_f32_16x16x32_bf16 v[52:55], v[148:151], v[166:169], v[52:55]
	v_mfma_f32_16x16x32_bf16 v[28:31], v[152:155], v[166:169], v[28:31]
	v_mfma_f32_16x16x32_bf16 v[12:15], v[244:247], v[166:169], v[12:15]
	v_mfma_f32_16x16x32_bf16 v[44:47], v[248:251], v[166:169], v[44:47]
	ds_read_b128 v[166:169], v186 offset:4096
	v_mfma_f32_16x16x32_bf16 v[48:51], v[148:151], v[170:173], v[48:51]
	v_mfma_f32_16x16x32_bf16 v[24:27], v[152:155], v[170:173], v[24:27]
	v_mfma_f32_16x16x32_bf16 v[8:11], v[244:247], v[170:173], v[8:11]
	v_mfma_f32_16x16x32_bf16 v[40:43], v[248:251], v[170:173], v[40:43]
	ds_read_b128 v[170:173], v186 offset:6144
	s_branch .LBB0_698
